# up GEMM: no store drain at the top of each unit (unit computation and prologue loads issue while the previous epilogue's write-through stores are acknowledged)
# baseline (speedup 1.0000x reference)
.LBB0_150:
	v_readlane_b32 s6, v254, 11
	s_mul_i32 s6, s48, s6
	s_mul_hi_u32 s7, s48, s81
	s_add_i32 s7, s7, s6
	s_mul_i32 s6, s48, s81
	v_readlane_b32 s9, v254, 2
	s_add_u32 s28, s6, s9
	v_readlane_b32 s6, v254, 22
	s_addc_u32 s29, s7, s6
	v_readlane_b32 s6, v255, 25
	v_readlane_b32 s7, v255, 26
	s_nop 0
	s_nop 0
	v_mov_b64_e32 v[2:3], s[6:7]
	v_cmp_ge_i64_e32 vcc, s[28:29], v[2:3]
	v_cmp_lt_i64_e64 s[6:7], s[28:29], v[2:3]
	s_cbranch_vccz .LBB0_152
	s_andn2_b64 vcc, exec, s[6:7]
	s_mov_b64 s[6:7], -1
	s_cbranch_vccnz .LBB0_149
	s_branch .LBB0_157
